# attention phase rewritten by hand: QK^T+softmax once per (b,map), PV over both value halves (1024 units)
# speedup vs baseline: 1.0621x; 1.0621x over previous
.LBB0_409:
	s_and_b64 vcc, exec, s[0:1]
	s_cbranch_vccz .LBB0_492
	v_readlane_b32 s0, v255, 12
	s_cmpk_gt_i32 s0, 0x7ff
	s_cbranch_scc1 .LBB0_492
	s_mov_b32 s24, m0
	v_readfirstlane_b32 s4, v198
	v_readlane_b32 s38, v255, 12
	s_lshr_b32 s27, s4, 6
	s_lshl_b32 s16, s27, 10
	v_and_b32_e32 v228, 31, v246
	v_lshrrev_b32_e32 v229, 5, v246
	v_lshlrev_b32_e32 v200, 10, v246
	s_lshl_b32 s4, s27, 4
	v_add_u32_e32 v200, s4, v200
	v_lshrrev_b32_e32 v230, 2, v246
	s_and_b32 s4, s27, 3
	s_lshl_b32 s4, s4, 4
	v_add_u32_e32 v230, s4, v230
	v_lshlrev_b32_e32 v230, 10, v230
	v_and_b32_e32 v231, 3, v246
	v_lshlrev_b32_e32 v231, 4, v231
	s_lshr_b32 s4, s27, 2
	s_lshl_b32 s4, s4, 6
	v_add3_u32 v201, v230, v231, s4
	v_add_u32_e32 v202, 0x80, v201
	s_lshl_b32 s4, s27, 5
	v_add_u32_e32 v230, s4, v228
	v_lshlrev_b32_e32 v225, 10, v230
	v_lshl_add_u32 v225, v229, 4, v225
	v_lshlrev_b32_e32 v231, 2, v229
	v_sub_u32_e32 v218, v230, v231
	v_lshlrev_b32_e32 v203, 10, v229
	v_lshl_add_u32 v203, v228, 4, v203
	v_bfe_u32 v230, v246, 4, 1
	v_lshlrev_b32_e32 v230, 5, v230
	v_and_b32_e32 v231, 3, v246
	v_lshl_add_u32 v230, v231, 3, v230
	v_bfe_u32 v231, v246, 2, 2
	v_lshl_add_u32 v231, v229, 2, v231
	v_lshl_add_u32 v230, v231, 6, v230
	v_add_u32_e32 v204, 0x6000, v230
	s_lshl_b32 s4, s27, 8
	s_add_i32 s4, s4, 0x12000
	v_lshl_add_u32 v220, v228, 2, s4
	v_lshl_add_u32 v221, v229, 4, s4
	s_lshl_b32 s4, s27, 12
	s_add_i32 s4, s4, 0x12800
	v_lshlrev_b32_e32 v230, 9, v229
	v_lshl_add_u32 v230, v228, 1, v230
	v_add_u32_e32 v222, s4, v230
	v_lshrrev_b32_e32 v230, 3, v246
	v_and_b32_e32 v231, 7, v246
	v_lshlrev_b32_e32 v223, 7, v230
	v_lshl_add_u32 v223, v231, 4, v223
	v_add_u32_e32 v223, s4, v223
	s_lshl_b32 s4, s27, 5
	v_add_u32_e32 v230, s4, v230
	v_lshlrev_b32_e32 v224, 11, v230
	v_lshl_add_u32 v224, v231, 4, v224
	v_mov_b32_e32 v219, 0xff800000
	v_mov_b32_e32 v211, 0
	v_mov_b32_e32 v213, 0
	s_mov_b32 s26, 0
.Lat2_unit_1:
	s_and_b32 s4, s38, 3
	s_lshl_b32 s4, s4, 1
	s_lshr_b32 s5, s26, 1
	s_add_i32 s4, s4, s5
	s_sub_i32 s5, 15, s4
	s_bitcmp1_b32 s26, 0
	s_cselect_b32 s4, s5, s4
	s_lshl_b32 s39, s4, 2
	s_add_i32 s39, s39, 4
	s_sub_i32 s18, s39, 4
	s_lshr_b32 s5, s38, 5
	s_lshl_b32 s5, s5, 12
	s_lshl_b32 s6, s4, 8
	s_add_i32 s6, s6, s5
	s_bfe_u32 s7, s38, 0x30002
	s_lshl_b32 s14, s6, 10
	s_lshl_b32 s15, s7, 7
	s_add_i32 s14, s14, s15
	s_add_u32 s72, s54, s14
	s_addc_u32 s73, s55, 0
	s_lshl_b32 s14, s5, 10
	s_add_i32 s15, s14, s15
	s_add_i32 s15, s15, 0x2000000
	s_add_u32 s74, s54, s15
	s_addc_u32 s75, s55, 0
	s_lshr_b32 s15, s7, 1
	s_lshl_b32 s15, s15, 8
	s_add_i32 s14, s14, s15
	s_add_u32 s76, s64, s14
	s_addc_u32 s77, s65, 0
	s_lshl_b32 s14, s6, 11
	s_lshl_b32 s15, s7, 8
	s_add_i32 s14, s14, s15
	s_add_u32 s78, s50, s14
	s_addc_u32 s79, s51, 0
	global_load_dwordx4 v[148:151], v225, s[72:73] offset:0
	global_load_dwordx4 v[152:155], v225, s[72:73] offset:32
	global_load_dwordx4 v[156:159], v225, s[72:73] offset:64
	global_load_dwordx4 v[160:163], v225, s[72:73] offset:96
	s_mov_b64 s[80:81], s[74:75]
	s_mov_b64 s[82:83], s[76:77]
	s_mov_b32 s59, 0
	s_mov_b32 s60, 0x2000
	s_mov_b32 s61, 0x4000
	s_add_i32 s4, s59, s16
	s_mov_b32 m0, s4
	s_lshl_b32 s5, s59, 1
	global_load_lds_dwordx4 v200, s[80:81]
	s_add_i32 s5, s5, s16
	s_add_i32 s5, s5, 0x6000
	s_mov_b32 m0, s5
	s_add_i32 s5, s5, 0x2000
	global_load_lds_dwordx4 v201, s[82:83]
	s_mov_b32 m0, s5
	s_nop 0
	global_load_lds_dwordx4 v202, s[82:83]
	s_add_u32 s80, s80, 0x10000
	s_addc_u32 s81, s81, 0
	s_add_u32 s82, s82, 0x10000
	s_addc_u32 s83, s83, 0
	s_add_i32 s4, s60, s16
	s_mov_b32 m0, s4
	s_lshl_b32 s5, s60, 1
	global_load_lds_dwordx4 v200, s[80:81]
	s_add_i32 s5, s5, s16
	s_add_i32 s5, s5, 0x6000
	s_mov_b32 m0, s5
	s_add_i32 s5, s5, 0x2000
	global_load_lds_dwordx4 v201, s[82:83]
	s_mov_b32 m0, s5
	s_nop 0
	global_load_lds_dwordx4 v202, s[82:83]
	s_add_u32 s80, s80, 0x10000
	s_addc_u32 s81, s81, 0
	s_add_u32 s82, s82, 0x10000
	s_addc_u32 s83, s83, 0
	v_mov_b32_e32 v0, 0
	v_mov_b32_e32 v1, 0
	v_mov_b32_e32 v2, 0
	v_mov_b32_e32 v3, 0
	v_mov_b32_e32 v4, 0
	v_mov_b32_e32 v5, 0
	v_mov_b32_e32 v6, 0
	v_mov_b32_e32 v7, 0
	v_mov_b32_e32 v8, 0
	v_mov_b32_e32 v9, 0
	v_mov_b32_e32 v10, 0
	v_mov_b32_e32 v11, 0
	v_mov_b32_e32 v12, 0
	v_mov_b32_e32 v13, 0
	v_mov_b32_e32 v14, 0
	v_mov_b32_e32 v15, 0
	v_mov_b32_e32 v16, 0
	v_mov_b32_e32 v17, 0
	v_mov_b32_e32 v18, 0
	v_mov_b32_e32 v19, 0
	v_mov_b32_e32 v20, 0
	v_mov_b32_e32 v21, 0
	v_mov_b32_e32 v22, 0
	v_mov_b32_e32 v23, 0
	v_mov_b32_e32 v24, 0
	v_mov_b32_e32 v25, 0
	v_mov_b32_e32 v26, 0
	v_mov_b32_e32 v27, 0
	v_mov_b32_e32 v28, 0
	v_mov_b32_e32 v29, 0
	v_mov_b32_e32 v30, 0
	v_mov_b32_e32 v31, 0
	v_mov_b32_e32 v32, 0
	v_mov_b32_e32 v33, 0
	v_mov_b32_e32 v34, 0
	v_mov_b32_e32 v35, 0
	v_mov_b32_e32 v36, 0
	v_mov_b32_e32 v37, 0
	v_mov_b32_e32 v38, 0
	v_mov_b32_e32 v39, 0
	v_mov_b32_e32 v40, 0
	v_mov_b32_e32 v41, 0
	v_mov_b32_e32 v42, 0
	v_mov_b32_e32 v43, 0
	v_mov_b32_e32 v44, 0
	v_mov_b32_e32 v45, 0
	v_mov_b32_e32 v46, 0
	v_mov_b32_e32 v47, 0
	v_mov_b32_e32 v48, 0
	v_mov_b32_e32 v49, 0
	v_mov_b32_e32 v50, 0
	v_mov_b32_e32 v51, 0
	v_mov_b32_e32 v52, 0
	v_mov_b32_e32 v53, 0
	v_mov_b32_e32 v54, 0
	v_mov_b32_e32 v55, 0
	v_mov_b32_e32 v56, 0
	v_mov_b32_e32 v57, 0
	v_mov_b32_e32 v58, 0
	v_mov_b32_e32 v59, 0
	v_mov_b32_e32 v60, 0
	v_mov_b32_e32 v61, 0
	v_mov_b32_e32 v62, 0
	v_mov_b32_e32 v63, 0
	v_mov_b32_e32 v210, 0
	v_mov_b32_e32 v208, 0
	v_mov_b32_e32 v209, 0
	s_mov_b32 s62, 0xf149f2ca
	s_mov_b32 s47, 0xf149f2ca
	s_mov_b32 s45, 0
	s_waitcnt vmcnt(3)
	s_barrier
.Lat2_main_2:
	s_cmp_lt_u32 s45, s18
	s_cbranch_scc0 .Lat2_band_3
	v_add_u32_e32 v205, s59, v203
	ds_read_b128 v[116:119], v205 offset:0
	ds_read_b128 v[120:123], v205 offset:512
	ds_read_b128 v[124:127], v205 offset:2048
	ds_read_b128 v[128:131], v205 offset:2560
	ds_read_b128 v[132:135], v205 offset:4096
	ds_read_b128 v[136:139], v205 offset:4608
	ds_read_b128 v[140:143], v205 offset:6144
	ds_read_b128 v[144:147], v205 offset:6656
	s_add_i32 s6, s45, 2
	s_cmp_lt_u32 s6, s39
	s_cbranch_scc0 .Lat2_nodma_6
	s_add_i32 s4, s61, s16
	s_mov_b32 m0, s4
	s_lshl_b32 s5, s61, 1
	global_load_lds_dwordx4 v200, s[80:81]
	s_add_i32 s5, s5, s16
	s_add_i32 s5, s5, 0x6000
	s_mov_b32 m0, s5
	s_add_i32 s5, s5, 0x2000
	global_load_lds_dwordx4 v201, s[82:83]
	s_mov_b32 m0, s5
	s_nop 0
	global_load_lds_dwordx4 v202, s[82:83]
	s_add_u32 s80, s80, 0x10000
	s_addc_u32 s81, s81, 0
	s_add_u32 s82, s82, 0x10000
	s_addc_u32 s83, s83, 0
.Lat2_nodma_6:
	s_lshl_b32 s7, s59, 1
	v_add_u32_e32 v206, s7, v204
	s_waitcnt lgkmcnt(6)
	v_mfma_f32_32x32x16_bf16 v[64:79], v[116:119], v[148:151], 0
	v_mfma_f32_32x32x16_bf16 v[80:95], v[120:123], v[148:151], 0
	s_waitcnt lgkmcnt(4)
	v_mfma_f32_32x32x16_bf16 v[64:79], v[124:127], v[152:155], v[64:79]
	v_mfma_f32_32x32x16_bf16 v[80:95], v[128:131], v[152:155], v[80:95]
	s_waitcnt lgkmcnt(2)
	v_mfma_f32_32x32x16_bf16 v[64:79], v[132:135], v[156:159], v[64:79]
	v_mfma_f32_32x32x16_bf16 v[80:95], v[136:139], v[156:159], v[80:95]
	s_waitcnt lgkmcnt(0)
	v_mfma_f32_32x32x16_bf16 v[64:79], v[140:143], v[160:163], v[64:79]
	v_mfma_f32_32x32x16_bf16 v[80:95], v[144:147], v[160:163], v[80:95]
	ds_read_b64_tr_b16 v[164:165], v206 offset:0
	ds_read_b64_tr_b16 v[166:167], v206 offset:512
	ds_read_b64_tr_b16 v[168:169], v206 offset:4096
	ds_read_b64_tr_b16 v[170:171], v206 offset:4608
	ds_read_b64_tr_b16 v[172:173], v206 offset:8192
	ds_read_b64_tr_b16 v[174:175], v206 offset:8704
	ds_read_b64_tr_b16 v[176:177], v206 offset:12288
	ds_read_b64_tr_b16 v[178:179], v206 offset:12800
	ds_read_b64_tr_b16 v[180:181], v206 offset:1024
	ds_read_b64_tr_b16 v[182:183], v206 offset:1536
	ds_read_b64_tr_b16 v[184:185], v206 offset:5120
	ds_read_b64_tr_b16 v[186:187], v206 offset:5632
	ds_read_b64_tr_b16 v[188:189], v206 offset:9216
	ds_read_b64_tr_b16 v[190:191], v206 offset:9728
	ds_read_b64_tr_b16 v[192:193], v206 offset:13312
	ds_read_b64_tr_b16 v[194:195], v206 offset:13824
	s_nop 0
	s_nop 0
	v_pk_add_f32 v[64:65], v[64:65], v[210:211] op_sel_hi:[1,0] neg_lo:[0,1] neg_hi:[0,1]
	v_pk_add_f32 v[66:67], v[66:67], v[210:211] op_sel_hi:[1,0] neg_lo:[0,1] neg_hi:[0,1]
	v_pk_add_f32 v[68:69], v[68:69], v[210:211] op_sel_hi:[1,0] neg_lo:[0,1] neg_hi:[0,1]
	v_pk_add_f32 v[70:71], v[70:71], v[210:211] op_sel_hi:[1,0] neg_lo:[0,1] neg_hi:[0,1]
	v_pk_add_f32 v[72:73], v[72:73], v[210:211] op_sel_hi:[1,0] neg_lo:[0,1] neg_hi:[0,1]
	v_pk_add_f32 v[74:75], v[74:75], v[210:211] op_sel_hi:[1,0] neg_lo:[0,1] neg_hi:[0,1]
	v_pk_add_f32 v[76:77], v[76:77], v[210:211] op_sel_hi:[1,0] neg_lo:[0,1] neg_hi:[0,1]
	v_pk_add_f32 v[78:79], v[78:79], v[210:211] op_sel_hi:[1,0] neg_lo:[0,1] neg_hi:[0,1]
	v_pk_add_f32 v[80:81], v[80:81], v[210:211] op_sel_hi:[1,0] neg_lo:[0,1] neg_hi:[0,1]
	v_pk_add_f32 v[82:83], v[82:83], v[210:211] op_sel_hi:[1,0] neg_lo:[0,1] neg_hi:[0,1]
	v_pk_add_f32 v[84:85], v[84:85], v[210:211] op_sel_hi:[1,0] neg_lo:[0,1] neg_hi:[0,1]
	v_pk_add_f32 v[86:87], v[86:87], v[210:211] op_sel_hi:[1,0] neg_lo:[0,1] neg_hi:[0,1]
	v_pk_add_f32 v[88:89], v[88:89], v[210:211] op_sel_hi:[1,0] neg_lo:[0,1] neg_hi:[0,1]
	v_pk_add_f32 v[90:91], v[90:91], v[210:211] op_sel_hi:[1,0] neg_lo:[0,1] neg_hi:[0,1]
	v_pk_add_f32 v[92:93], v[92:93], v[210:211] op_sel_hi:[1,0] neg_lo:[0,1] neg_hi:[0,1]
	v_pk_add_f32 v[94:95], v[94:95], v[210:211] op_sel_hi:[1,0] neg_lo:[0,1] neg_hi:[0,1]
	v_max3_f32 v215, v64, v65, v80
	v_max3_f32 v216, v66, v67, v81
	v_max3_f32 v215, v215, v82, v83
	v_max3_f32 v216, v216, v68, v69
	v_max3_f32 v215, v215, v70, v71
	v_max3_f32 v216, v216, v84, v85
	v_max3_f32 v215, v215, v86, v87
	v_max3_f32 v216, v216, v72, v73
	v_max3_f32 v215, v215, v74, v75
	v_max3_f32 v216, v216, v88, v89
	v_max3_f32 v215, v215, v90, v91
	v_max3_f32 v216, v216, v76, v77
	v_max3_f32 v215, v215, v78, v79
	v_max3_f32 v216, v216, v92, v93
	v_max3_f32 v215, v215, v94, v95
	v_max_f32_e32 v214, v215, v216
	v_mov_b32_e32 v215, v214
	s_nop 1
	v_permlane32_swap_b32_e32 v214, v215
	s_nop 0
	v_max_f32_e32 v214, v214, v215
	v_cmp_lt_f32_e32 vcc, s62, v214
	s_cmp_lg_u64 vcc, 0
	s_cbranch_scc1 .Lat2_resc_7
.Lat2_back_8:
	v_exp_f32_e32 v64, v64
	v_exp_f32_e32 v65, v65
	v_exp_f32_e32 v66, v66
	v_exp_f32_e32 v67, v67
	v_exp_f32_e32 v68, v68
	v_exp_f32_e32 v69, v69
	v_exp_f32_e32 v70, v70
	v_exp_f32_e32 v71, v71
	s_nop 0
	v_cvt_pk_bf16_f32 v100, v64, v65
	v_cvt_pk_bf16_f32 v101, v66, v67
	v_cvt_pk_bf16_f32 v102, v68, v69
	v_cvt_pk_bf16_f32 v103, v70, v71
	v_pk_add_f32 v[208:209], v[208:209], v[64:65]
	v_pk_add_f32 v[208:209], v[208:209], v[66:67]
	s_waitcnt lgkmcnt(0)
	v_mfma_f32_32x32x16_bf16 v[0:15], v[100:103], v[164:167], v[0:15]
	v_exp_f32_e32 v72, v72
	v_exp_f32_e32 v73, v73
	v_mfma_f32_32x32x16_bf16 v[16:31], v[100:103], v[168:171], v[16:31]
	ds_read_b64_tr_b16 v[164:165], v206 offset:2048
	ds_read_b64_tr_b16 v[166:167], v206 offset:2560
	v_exp_f32_e32 v74, v74
	v_exp_f32_e32 v75, v75
	v_pk_add_f32 v[208:209], v[208:209], v[68:69]
	v_mfma_f32_32x32x16_bf16 v[32:47], v[100:103], v[172:175], v[32:47]
	ds_read_b64_tr_b16 v[168:169], v206 offset:6144
	ds_read_b64_tr_b16 v[170:171], v206 offset:6656
	v_exp_f32_e32 v76, v76
	v_exp_f32_e32 v77, v77
	v_pk_add_f32 v[208:209], v[208:209], v[70:71]
	v_mfma_f32_32x32x16_bf16 v[48:63], v[100:103], v[176:179], v[48:63]
	ds_read_b64_tr_b16 v[172:173], v206 offset:10240
	ds_read_b64_tr_b16 v[174:175], v206 offset:10752
	v_exp_f32_e32 v78, v78
	v_exp_f32_e32 v79, v79
	s_nop 0
	v_cvt_pk_bf16_f32 v104, v72, v73
	v_cvt_pk_bf16_f32 v105, v74, v75
	v_cvt_pk_bf16_f32 v106, v76, v77
	v_cvt_pk_bf16_f32 v107, v78, v79
	v_pk_add_f32 v[208:209], v[208:209], v[72:73]
	v_pk_add_f32 v[208:209], v[208:209], v[74:75]
	v_mfma_f32_32x32x16_bf16 v[0:15], v[104:107], v[180:183], v[0:15]
	ds_read_b64_tr_b16 v[176:177], v206 offset:14336
	ds_read_b64_tr_b16 v[178:179], v206 offset:14848
	v_exp_f32_e32 v80, v80
	v_exp_f32_e32 v81, v81
	v_mfma_f32_32x32x16_bf16 v[16:31], v[104:107], v[184:187], v[16:31]
	ds_read_b64_tr_b16 v[180:181], v206 offset:3072
	ds_read_b64_tr_b16 v[182:183], v206 offset:3584
	v_exp_f32_e32 v82, v82
	v_exp_f32_e32 v83, v83
	v_pk_add_f32 v[208:209], v[208:209], v[76:77]
	v_mfma_f32_32x32x16_bf16 v[32:47], v[104:107], v[188:191], v[32:47]
	ds_read_b64_tr_b16 v[184:185], v206 offset:7168
	ds_read_b64_tr_b16 v[186:187], v206 offset:7680
	v_exp_f32_e32 v84, v84
	v_exp_f32_e32 v85, v85
	v_pk_add_f32 v[208:209], v[208:209], v[78:79]
	v_mfma_f32_32x32x16_bf16 v[48:63], v[104:107], v[192:195], v[48:63]
	ds_read_b64_tr_b16 v[188:189], v206 offset:11264
	ds_read_b64_tr_b16 v[190:191], v206 offset:11776
	v_exp_f32_e32 v86, v86
	v_exp_f32_e32 v87, v87
	s_nop 0
	v_cvt_pk_bf16_f32 v108, v80, v81
	v_cvt_pk_bf16_f32 v109, v82, v83
	v_cvt_pk_bf16_f32 v110, v84, v85
	v_cvt_pk_bf16_f32 v111, v86, v87
	v_pk_add_f32 v[208:209], v[208:209], v[80:81]
	v_pk_add_f32 v[208:209], v[208:209], v[82:83]
	s_waitcnt lgkmcnt(12)
	v_mfma_f32_32x32x16_bf16 v[0:15], v[108:111], v[164:167], v[0:15]
	ds_read_b64_tr_b16 v[192:193], v206 offset:15360
	ds_read_b64_tr_b16 v[194:195], v206 offset:15872
	v_exp_f32_e32 v88, v88
	v_exp_f32_e32 v89, v89
	s_waitcnt lgkmcnt(12)
	v_mfma_f32_32x32x16_bf16 v[16:31], v[108:111], v[168:171], v[16:31]
	v_exp_f32_e32 v90, v90
	v_exp_f32_e32 v91, v91
	v_pk_add_f32 v[208:209], v[208:209], v[84:85]
	s_waitcnt lgkmcnt(10)
	v_mfma_f32_32x32x16_bf16 v[32:47], v[108:111], v[172:175], v[32:47]
	v_exp_f32_e32 v92, v92
	v_exp_f32_e32 v93, v93
	v_pk_add_f32 v[208:209], v[208:209], v[86:87]
	s_waitcnt lgkmcnt(8)
	v_mfma_f32_32x32x16_bf16 v[48:63], v[108:111], v[176:179], v[48:63]
	v_exp_f32_e32 v94, v94
	v_exp_f32_e32 v95, v95
	s_nop 0
	v_cvt_pk_bf16_f32 v112, v88, v89
	v_cvt_pk_bf16_f32 v113, v90, v91
	v_cvt_pk_bf16_f32 v114, v92, v93
	v_cvt_pk_bf16_f32 v115, v94, v95
	v_pk_add_f32 v[208:209], v[208:209], v[88:89]
	v_pk_add_f32 v[208:209], v[208:209], v[90:91]
	s_waitcnt lgkmcnt(6)
	v_mfma_f32_32x32x16_bf16 v[0:15], v[112:115], v[180:183], v[0:15]
	s_waitcnt lgkmcnt(4)
	v_mfma_f32_32x32x16_bf16 v[16:31], v[112:115], v[184:187], v[16:31]
	s_waitcnt lgkmcnt(2)
	v_mfma_f32_32x32x16_bf16 v[32:47], v[112:115], v[188:191], v[32:47]
	s_waitcnt lgkmcnt(0)
	v_mfma_f32_32x32x16_bf16 v[48:63], v[112:115], v[192:195], v[48:63]
	v_pk_add_f32 v[208:209], v[208:209], v[92:93]
	v_pk_add_f32 v[208:209], v[208:209], v[94:95]
	s_add_i32 s6, s45, 2
	s_cmp_lt_u32 s6, s39
	s_cbranch_scc1 .Lat2_w3_9
	s_waitcnt vmcnt(0)
	s_branch .Lat2_wd_10
.Lat2_w3_9:
	s_waitcnt vmcnt(3)
.Lat2_wd_10:
	s_waitcnt lgkmcnt(0)
	s_barrier
	s_mov_b32 s4, s59
	s_mov_b32 s59, s60
	s_mov_b32 s60, s61
	s_mov_b32 s61, s4
	s_add_i32 s45, s45, 1
	s_mov_b32 s62, 0x41000000
	s_mov_b32 s47, 0
	s_branch .Lat2_main_2
.Lat2_band_3:
.Lat2_bandloop_4:
	s_sub_i32 s19, s45, s18
	v_add_u32_e32 v205, s59, v203
	ds_read_b128 v[116:119], v205 offset:0
	ds_read_b128 v[120:123], v205 offset:512
	ds_read_b128 v[124:127], v205 offset:2048
	ds_read_b128 v[128:131], v205 offset:2560
	ds_read_b128 v[132:135], v205 offset:4096
	ds_read_b128 v[136:139], v205 offset:4608
	ds_read_b128 v[140:143], v205 offset:6144
	ds_read_b128 v[144:147], v205 offset:6656
	s_add_i32 s6, s45, 2
	s_cmp_lt_u32 s6, s39
	s_cbranch_scc0 .Lat2_nodma_11
	s_add_i32 s4, s61, s16
	s_mov_b32 m0, s4
	s_lshl_b32 s5, s61, 1
	global_load_lds_dwordx4 v200, s[80:81]
	s_add_i32 s5, s5, s16
	s_add_i32 s5, s5, 0x6000
	s_mov_b32 m0, s5
	s_add_i32 s5, s5, 0x2000
	global_load_lds_dwordx4 v201, s[82:83]
	s_mov_b32 m0, s5
	s_nop 0
	global_load_lds_dwordx4 v202, s[82:83]
	s_add_u32 s80, s80, 0x10000
	s_addc_u32 s81, s81, 0
	s_add_u32 s82, s82, 0x10000
	s_addc_u32 s83, s83, 0
.Lat2_nodma_11:
	s_lshl_b32 s7, s59, 1
	v_add_u32_e32 v206, s7, v204
	s_waitcnt lgkmcnt(6)
	v_mfma_f32_32x32x16_bf16 v[64:79], v[116:119], v[148:151], 0
	v_mfma_f32_32x32x16_bf16 v[80:95], v[120:123], v[148:151], 0
	s_waitcnt lgkmcnt(4)
	v_mfma_f32_32x32x16_bf16 v[64:79], v[124:127], v[152:155], v[64:79]
	v_mfma_f32_32x32x16_bf16 v[80:95], v[128:131], v[152:155], v[80:95]
	s_waitcnt lgkmcnt(2)
	v_mfma_f32_32x32x16_bf16 v[64:79], v[132:135], v[156:159], v[64:79]
	v_mfma_f32_32x32x16_bf16 v[80:95], v[136:139], v[156:159], v[80:95]
	s_waitcnt lgkmcnt(0)
	v_mfma_f32_32x32x16_bf16 v[64:79], v[140:143], v[160:163], v[64:79]
	v_mfma_f32_32x32x16_bf16 v[80:95], v[144:147], v[160:163], v[80:95]
	ds_read_b64_tr_b16 v[164:165], v206 offset:0
	ds_read_b64_tr_b16 v[166:167], v206 offset:512
	ds_read_b64_tr_b16 v[168:169], v206 offset:4096
	ds_read_b64_tr_b16 v[170:171], v206 offset:4608
	ds_read_b64_tr_b16 v[172:173], v206 offset:8192
	ds_read_b64_tr_b16 v[174:175], v206 offset:8704
	ds_read_b64_tr_b16 v[176:177], v206 offset:12288
	ds_read_b64_tr_b16 v[178:179], v206 offset:12800
	ds_read_b64_tr_b16 v[180:181], v206 offset:1024
	ds_read_b64_tr_b16 v[182:183], v206 offset:1536
	ds_read_b64_tr_b16 v[184:185], v206 offset:5120
	ds_read_b64_tr_b16 v[186:187], v206 offset:5632
	ds_read_b64_tr_b16 v[188:189], v206 offset:9216
	ds_read_b64_tr_b16 v[190:191], v206 offset:9728
	ds_read_b64_tr_b16 v[192:193], v206 offset:13312
	ds_read_b64_tr_b16 v[194:195], v206 offset:13824
	s_lshl_b32 s7, s19, 6
	v_subrev_u32_e32 v226, s7, v218
	v_pk_add_f32 v[64:65], v[64:65], v[210:211] op_sel_hi:[1,0] neg_lo:[0,1] neg_hi:[0,1]
	v_pk_add_f32 v[66:67], v[66:67], v[210:211] op_sel_hi:[1,0] neg_lo:[0,1] neg_hi:[0,1]
	v_pk_add_f32 v[68:69], v[68:69], v[210:211] op_sel_hi:[1,0] neg_lo:[0,1] neg_hi:[0,1]
	v_pk_add_f32 v[70:71], v[70:71], v[210:211] op_sel_hi:[1,0] neg_lo:[0,1] neg_hi:[0,1]
	v_pk_add_f32 v[72:73], v[72:73], v[210:211] op_sel_hi:[1,0] neg_lo:[0,1] neg_hi:[0,1]
	v_pk_add_f32 v[74:75], v[74:75], v[210:211] op_sel_hi:[1,0] neg_lo:[0,1] neg_hi:[0,1]
	v_pk_add_f32 v[76:77], v[76:77], v[210:211] op_sel_hi:[1,0] neg_lo:[0,1] neg_hi:[0,1]
	v_pk_add_f32 v[78:79], v[78:79], v[210:211] op_sel_hi:[1,0] neg_lo:[0,1] neg_hi:[0,1]
	v_pk_add_f32 v[80:81], v[80:81], v[210:211] op_sel_hi:[1,0] neg_lo:[0,1] neg_hi:[0,1]
	v_pk_add_f32 v[82:83], v[82:83], v[210:211] op_sel_hi:[1,0] neg_lo:[0,1] neg_hi:[0,1]
	v_pk_add_f32 v[84:85], v[84:85], v[210:211] op_sel_hi:[1,0] neg_lo:[0,1] neg_hi:[0,1]
	v_pk_add_f32 v[86:87], v[86:87], v[210:211] op_sel_hi:[1,0] neg_lo:[0,1] neg_hi:[0,1]
	v_pk_add_f32 v[88:89], v[88:89], v[210:211] op_sel_hi:[1,0] neg_lo:[0,1] neg_hi:[0,1]
	v_pk_add_f32 v[90:91], v[90:91], v[210:211] op_sel_hi:[1,0] neg_lo:[0,1] neg_hi:[0,1]
	v_pk_add_f32 v[92:93], v[92:93], v[210:211] op_sel_hi:[1,0] neg_lo:[0,1] neg_hi:[0,1]
	v_pk_add_f32 v[94:95], v[94:95], v[210:211] op_sel_hi:[1,0] neg_lo:[0,1] neg_hi:[0,1]
	v_cmp_gt_i32_e64 s[0:1], 0, v226
	v_cmp_gt_i32_e64 s[14:15], 1, v226
	v_cmp_gt_i32_e64 vcc, 2, v226
	v_cndmask_b32_e64 v64, v64, v219, s[0:1]
	v_cmp_gt_i32_e64 s[0:1], 3, v226
	v_cndmask_b32_e64 v65, v65, v219, s[14:15]
	v_cmp_gt_i32_e64 s[14:15], 8, v226
	v_cndmask_b32_e64 v66, v66, v219, vcc
	v_cmp_gt_i32_e64 vcc, 9, v226
	v_cndmask_b32_e64 v67, v67, v219, s[0:1]
	v_cmp_gt_i32_e64 s[0:1], 10, v226
	v_cndmask_b32_e64 v68, v68, v219, s[14:15]
	v_cmp_gt_i32_e64 s[14:15], 11, v226
	v_cndmask_b32_e64 v69, v69, v219, vcc
	v_cmp_gt_i32_e64 vcc, 16, v226
	v_cndmask_b32_e64 v70, v70, v219, s[0:1]
	v_cmp_gt_i32_e64 s[0:1], 17, v226
	v_cndmask_b32_e64 v71, v71, v219, s[14:15]
	v_cmp_gt_i32_e64 s[14:15], 18, v226
	v_cndmask_b32_e64 v72, v72, v219, vcc
	v_cmp_gt_i32_e64 vcc, 19, v226
	v_cndmask_b32_e64 v73, v73, v219, s[0:1]
	v_cmp_gt_i32_e64 s[0:1], 24, v226
	v_cndmask_b32_e64 v74, v74, v219, s[14:15]
	v_cmp_gt_i32_e64 s[14:15], 25, v226
	v_cndmask_b32_e64 v75, v75, v219, vcc
	v_cmp_gt_i32_e64 vcc, 26, v226
	v_cndmask_b32_e64 v76, v76, v219, s[0:1]
	v_cmp_gt_i32_e64 s[0:1], 27, v226
	v_cndmask_b32_e64 v77, v77, v219, s[14:15]
	v_cmp_gt_i32_e64 s[14:15], 32, v226
	v_cndmask_b32_e64 v78, v78, v219, vcc
	v_cmp_gt_i32_e64 vcc, 33, v226
	v_cndmask_b32_e64 v79, v79, v219, s[0:1]
	v_cmp_gt_i32_e64 s[0:1], 34, v226
	v_cndmask_b32_e64 v80, v80, v219, s[14:15]
	v_cmp_gt_i32_e64 s[14:15], 35, v226
	v_cndmask_b32_e64 v81, v81, v219, vcc
	v_cmp_gt_i32_e64 vcc, 40, v226
	v_cndmask_b32_e64 v82, v82, v219, s[0:1]
	v_cmp_gt_i32_e64 s[0:1], 41, v226
	v_cndmask_b32_e64 v83, v83, v219, s[14:15]
	v_cmp_gt_i32_e64 s[14:15], 42, v226
	v_cndmask_b32_e64 v84, v84, v219, vcc
	v_cmp_gt_i32_e64 vcc, 43, v226
	v_cndmask_b32_e64 v85, v85, v219, s[0:1]
	v_cmp_gt_i32_e64 s[0:1], 48, v226
	v_cndmask_b32_e64 v86, v86, v219, s[14:15]
	v_cmp_gt_i32_e64 s[14:15], 49, v226
	v_cndmask_b32_e64 v87, v87, v219, vcc
	v_cmp_gt_i32_e64 vcc, 50, v226
	v_cndmask_b32_e64 v88, v88, v219, s[0:1]
	v_cmp_gt_i32_e64 s[0:1], 51, v226
	v_cndmask_b32_e64 v89, v89, v219, s[14:15]
	v_cmp_gt_i32_e64 s[14:15], 56, v226
	v_cndmask_b32_e64 v90, v90, v219, vcc
	v_cmp_gt_i32_e64 vcc, 57, v226
	v_cndmask_b32_e64 v91, v91, v219, s[0:1]
	v_cmp_gt_i32_e64 s[0:1], 58, v226
	v_cndmask_b32_e64 v92, v92, v219, s[14:15]
	v_cmp_gt_i32_e64 s[14:15], 59, v226
	v_cndmask_b32_e64 v93, v93, v219, vcc
	s_nop 0
	v_cndmask_b32_e64 v94, v94, v219, s[0:1]
	s_nop 0
	v_cndmask_b32_e64 v95, v95, v219, s[14:15]
	v_max3_f32 v215, v64, v65, v80
	v_max3_f32 v216, v66, v67, v81
	v_max3_f32 v215, v215, v82, v83
	v_max3_f32 v216, v216, v68, v69
	v_max3_f32 v215, v215, v70, v71
	v_max3_f32 v216, v216, v84, v85
	v_max3_f32 v215, v215, v86, v87
	v_max3_f32 v216, v216, v72, v73
	v_max3_f32 v215, v215, v74, v75
	v_max3_f32 v216, v216, v88, v89
	v_max3_f32 v215, v215, v90, v91
	v_max3_f32 v216, v216, v76, v77
	v_max3_f32 v215, v215, v78, v79
	v_max3_f32 v216, v216, v92, v93
	v_max3_f32 v215, v215, v94, v95
	v_max_f32_e32 v214, v215, v216
	v_mov_b32_e32 v215, v214
	s_nop 1
	v_permlane32_swap_b32_e32 v214, v215
	s_nop 0
	v_max_f32_e32 v214, v214, v215
	v_cmp_lt_f32_e32 vcc, s62, v214
	s_cmp_lg_u64 vcc, 0
	s_cbranch_scc1 .Lat2_resc_12

.Lat2_wd_15:
	s_waitcnt lgkmcnt(0)
	s_barrier
	s_mov_b32 s4, s59
	s_mov_b32 s59, s60
	s_mov_b32 s60, s61
	s_mov_b32 s61, s4
	s_add_i32 s45, s45, 1
	s_mov_b32 s62, 0x41000000
	s_mov_b32 s47, 0
	s_cmp_lt_u32 s45, s39
	s_cbranch_scc1 .Lat2_bandloop_4
	v_add_f32_e32 v216, v208, v209
	v_mov_b32_e32 v215, v216
	s_nop 1
	v_permlane32_swap_b32_e32 v216, v215
	s_nop 0
	v_add_f32_e32 v216, v216, v215
	v_rcp_f32_e32 v217, v216
	s_nop 0
	ds_write_b32 v220, v217
	s_waitcnt lgkmcnt(0)
	ds_read_b128 v[116:119], v221 offset:0
	ds_read_b128 v[120:123], v221 offset:32
	ds_read_b128 v[124:127], v221 offset:64
	ds_read_b128 v[128:131], v221 offset:96
	s_waitcnt lgkmcnt(0)
	v_mul_f32_e32 v0, v0, v116
	v_mul_f32_e32 v1, v1, v117
	v_cvt_pk_bf16_f32 v0, v0, v1
	ds_write_b16 v222, v0 offset:0
	ds_write_b16_d16_hi v222, v0 offset:128
	v_mul_f32_e32 v2, v2, v118
	v_mul_f32_e32 v3, v3, v119
	v_cvt_pk_bf16_f32 v2, v2, v3
	ds_write_b16 v222, v2 offset:256
	ds_write_b16_d16_hi v222, v2 offset:384
	v_mul_f32_e32 v4, v4, v120
	v_mul_f32_e32 v5, v5, v121
	v_cvt_pk_bf16_f32 v4, v4, v5
	ds_write_b16 v222, v4 offset:1024
	ds_write_b16_d16_hi v222, v4 offset:1152
	v_mul_f32_e32 v6, v6, v122
	v_mul_f32_e32 v7, v7, v123
	v_cvt_pk_bf16_f32 v6, v6, v7
	ds_write_b16 v222, v6 offset:1280
	ds_write_b16_d16_hi v222, v6 offset:1408
	v_mul_f32_e32 v8, v8, v124
	v_mul_f32_e32 v9, v9, v125
	v_cvt_pk_bf16_f32 v8, v8, v9
	ds_write_b16 v222, v8 offset:2048
	ds_write_b16_d16_hi v222, v8 offset:2176
	v_mul_f32_e32 v10, v10, v126
	v_mul_f32_e32 v11, v11, v127
	v_cvt_pk_bf16_f32 v10, v10, v11
	ds_write_b16 v222, v10 offset:2304
	ds_write_b16_d16_hi v222, v10 offset:2432
	v_mul_f32_e32 v12, v12, v128
	v_mul_f32_e32 v13, v13, v129
	v_cvt_pk_bf16_f32 v12, v12, v13
	ds_write_b16 v222, v12 offset:3072
	ds_write_b16_d16_hi v222, v12 offset:3200
	v_mul_f32_e32 v14, v14, v130
	v_mul_f32_e32 v15, v15, v131
	v_cvt_pk_bf16_f32 v14, v14, v15
	ds_write_b16 v222, v14 offset:3328
	ds_write_b16_d16_hi v222, v14 offset:3456
	v_mul_f32_e32 v16, v16, v116
	v_mul_f32_e32 v17, v17, v117
	v_cvt_pk_bf16_f32 v16, v16, v17
	ds_write_b16 v222, v16 offset:64
	ds_write_b16_d16_hi v222, v16 offset:192
	v_mul_f32_e32 v18, v18, v118
	v_mul_f32_e32 v19, v19, v119
	v_cvt_pk_bf16_f32 v18, v18, v19
	ds_write_b16 v222, v18 offset:320
	ds_write_b16_d16_hi v222, v18 offset:448
	v_mul_f32_e32 v20, v20, v120
	v_mul_f32_e32 v21, v21, v121
	v_cvt_pk_bf16_f32 v20, v20, v21
	ds_write_b16 v222, v20 offset:1088
	ds_write_b16_d16_hi v222, v20 offset:1216
	v_mul_f32_e32 v22, v22, v122
	v_mul_f32_e32 v23, v23, v123
	v_cvt_pk_bf16_f32 v22, v22, v23
	ds_write_b16 v222, v22 offset:1344
	ds_write_b16_d16_hi v222, v22 offset:1472
	v_mul_f32_e32 v24, v24, v124
	v_mul_f32_e32 v25, v25, v125
	v_cvt_pk_bf16_f32 v24, v24, v25
	ds_write_b16 v222, v24 offset:2112
	ds_write_b16_d16_hi v222, v24 offset:2240
	v_mul_f32_e32 v26, v26, v126
	v_mul_f32_e32 v27, v27, v127
	v_cvt_pk_bf16_f32 v26, v26, v27
	ds_write_b16 v222, v26 offset:2368
	ds_write_b16_d16_hi v222, v26 offset:2496
	v_mul_f32_e32 v28, v28, v128
	v_mul_f32_e32 v29, v29, v129
	v_cvt_pk_bf16_f32 v28, v28, v29
	ds_write_b16 v222, v28 offset:3136
	ds_write_b16_d16_hi v222, v28 offset:3264
	v_mul_f32_e32 v30, v30, v130
	v_mul_f32_e32 v31, v31, v131
	v_cvt_pk_bf16_f32 v30, v30, v31
	ds_write_b16 v222, v30 offset:3392
	ds_write_b16_d16_hi v222, v30 offset:3520
	s_waitcnt lgkmcnt(0)
	ds_read_b128 v[132:135], v223 offset:0
	ds_read_b128 v[136:139], v223 offset:1024
	ds_read_b128 v[140:143], v223 offset:2048
	ds_read_b128 v[144:147], v223 offset:3072
	v_add_u32_e32 v228, 0x0, v224
	v_add_u32_e32 v229, 0x4000, v224
	v_add_u32_e32 v230, 0x8000, v224
	v_add_u32_e32 v231, 0xc000, v224
	s_waitcnt lgkmcnt(3)
	global_store_dwordx4 v228, v[132:135], s[78:79] offset:0
	s_waitcnt lgkmcnt(2)
	global_store_dwordx4 v229, v[136:139], s[78:79] offset:0
	s_waitcnt lgkmcnt(1)
	global_store_dwordx4 v230, v[140:143], s[78:79] offset:0
	s_waitcnt lgkmcnt(0)
	global_store_dwordx4 v231, v[144:147], s[78:79] offset:0
	v_mul_f32_e32 v32, v32, v116
	v_mul_f32_e32 v33, v33, v117
	v_cvt_pk_bf16_f32 v32, v32, v33
	ds_write_b16 v222, v32 offset:0
	ds_write_b16_d16_hi v222, v32 offset:128
	v_mul_f32_e32 v34, v34, v118
	v_mul_f32_e32 v35, v35, v119
	v_cvt_pk_bf16_f32 v34, v34, v35
	ds_write_b16 v222, v34 offset:256
	ds_write_b16_d16_hi v222, v34 offset:384
	v_mul_f32_e32 v36, v36, v120
	v_mul_f32_e32 v37, v37, v121
	v_cvt_pk_bf16_f32 v36, v36, v37
	ds_write_b16 v222, v36 offset:1024
	ds_write_b16_d16_hi v222, v36 offset:1152
	v_mul_f32_e32 v38, v38, v122
	v_mul_f32_e32 v39, v39, v123
	v_cvt_pk_bf16_f32 v38, v38, v39
	ds_write_b16 v222, v38 offset:1280
	ds_write_b16_d16_hi v222, v38 offset:1408
	v_mul_f32_e32 v40, v40, v124
	v_mul_f32_e32 v41, v41, v125
	v_cvt_pk_bf16_f32 v40, v40, v41
	ds_write_b16 v222, v40 offset:2048
	ds_write_b16_d16_hi v222, v40 offset:2176
	v_mul_f32_e32 v42, v42, v126
	v_mul_f32_e32 v43, v43, v127
	v_cvt_pk_bf16_f32 v42, v42, v43
	ds_write_b16 v222, v42 offset:2304
	ds_write_b16_d16_hi v222, v42 offset:2432
	v_mul_f32_e32 v44, v44, v128
	v_mul_f32_e32 v45, v45, v129
	v_cvt_pk_bf16_f32 v44, v44, v45
	ds_write_b16 v222, v44 offset:3072
	ds_write_b16_d16_hi v222, v44 offset:3200
	v_mul_f32_e32 v46, v46, v130
	v_mul_f32_e32 v47, v47, v131
	v_cvt_pk_bf16_f32 v46, v46, v47
	ds_write_b16 v222, v46 offset:3328
	ds_write_b16_d16_hi v222, v46 offset:3456
	v_mul_f32_e32 v48, v48, v116
	v_mul_f32_e32 v49, v49, v117
	v_cvt_pk_bf16_f32 v48, v48, v49
	ds_write_b16 v222, v48 offset:64
	ds_write_b16_d16_hi v222, v48 offset:192
	v_mul_f32_e32 v50, v50, v118
	v_mul_f32_e32 v51, v51, v119
	v_cvt_pk_bf16_f32 v50, v50, v51
	ds_write_b16 v222, v50 offset:320
	ds_write_b16_d16_hi v222, v50 offset:448
	v_mul_f32_e32 v52, v52, v120
	v_mul_f32_e32 v53, v53, v121
	v_cvt_pk_bf16_f32 v52, v52, v53
	ds_write_b16 v222, v52 offset:1088
	ds_write_b16_d16_hi v222, v52 offset:1216
	v_mul_f32_e32 v54, v54, v122
	v_mul_f32_e32 v55, v55, v123
	v_cvt_pk_bf16_f32 v54, v54, v55
	ds_write_b16 v222, v54 offset:1344
	ds_write_b16_d16_hi v222, v54 offset:1472
	v_mul_f32_e32 v56, v56, v124
	v_mul_f32_e32 v57, v57, v125
	v_cvt_pk_bf16_f32 v56, v56, v57
	ds_write_b16 v222, v56 offset:2112
	ds_write_b16_d16_hi v222, v56 offset:2240
	v_mul_f32_e32 v58, v58, v126
	v_mul_f32_e32 v59, v59, v127
	v_cvt_pk_bf16_f32 v58, v58, v59
	ds_write_b16 v222, v58 offset:2368
	ds_write_b16_d16_hi v222, v58 offset:2496
	v_mul_f32_e32 v60, v60, v128
	v_mul_f32_e32 v61, v61, v129
	v_cvt_pk_bf16_f32 v60, v60, v61
	ds_write_b16 v222, v60 offset:3136
	ds_write_b16_d16_hi v222, v60 offset:3264
	v_mul_f32_e32 v62, v62, v130
	v_mul_f32_e32 v63, v63, v131
	v_cvt_pk_bf16_f32 v62, v62, v63
	ds_write_b16 v222, v62 offset:3392
	ds_write_b16_d16_hi v222, v62 offset:3520
	s_waitcnt lgkmcnt(0)
	ds_read_b128 v[132:135], v223 offset:0
	ds_read_b128 v[136:139], v223 offset:1024
	ds_read_b128 v[140:143], v223 offset:2048
	ds_read_b128 v[144:147], v223 offset:3072
	v_add_u32_e32 v228, 0x0, v224
	v_add_u32_e32 v229, 0x4000, v224
	v_add_u32_e32 v230, 0x8000, v224
	v_add_u32_e32 v231, 0xc000, v224
	s_waitcnt lgkmcnt(3)
	global_store_dwordx4 v228, v[132:135], s[78:79] offset:128
	s_waitcnt lgkmcnt(2)
	global_store_dwordx4 v229, v[136:139], s[78:79] offset:128
	s_waitcnt lgkmcnt(1)
	global_store_dwordx4 v230, v[140:143], s[78:79] offset:128
	s_waitcnt lgkmcnt(0)
	global_store_dwordx4 v231, v[144:147], s[78:79] offset:128
	s_add_i32 s26, s26, 1
	s_cmp_lt_u32 s26, 4
	s_cbranch_scc1 .Lat2_unit_1
	s_branch .Lat2_done_5
.Lat2_resc_7:
	v_max_f32_e32 v212, s47, v214
	v_add_f32_e32 v210, v210, v212
	v_exp_f32_e64 v217, -v212
	v_pk_add_f32 v[64:65], v[64:65], v[212:213] op_sel_hi:[1,0] neg_lo:[0,1] neg_hi:[0,1]
	v_pk_add_f32 v[66:67], v[66:67], v[212:213] op_sel_hi:[1,0] neg_lo:[0,1] neg_hi:[0,1]
	v_pk_add_f32 v[68:69], v[68:69], v[212:213] op_sel_hi:[1,0] neg_lo:[0,1] neg_hi:[0,1]
	v_pk_add_f32 v[70:71], v[70:71], v[212:213] op_sel_hi:[1,0] neg_lo:[0,1] neg_hi:[0,1]
	v_pk_add_f32 v[72:73], v[72:73], v[212:213] op_sel_hi:[1,0] neg_lo:[0,1] neg_hi:[0,1]
	v_pk_add_f32 v[74:75], v[74:75], v[212:213] op_sel_hi:[1,0] neg_lo:[0,1] neg_hi:[0,1]
	v_pk_add_f32 v[76:77], v[76:77], v[212:213] op_sel_hi:[1,0] neg_lo:[0,1] neg_hi:[0,1]
	v_pk_add_f32 v[78:79], v[78:79], v[212:213] op_sel_hi:[1,0] neg_lo:[0,1] neg_hi:[0,1]
	v_pk_add_f32 v[80:81], v[80:81], v[212:213] op_sel_hi:[1,0] neg_lo:[0,1] neg_hi:[0,1]
	v_pk_add_f32 v[82:83], v[82:83], v[212:213] op_sel_hi:[1,0] neg_lo:[0,1] neg_hi:[0,1]
	v_pk_add_f32 v[84:85], v[84:85], v[212:213] op_sel_hi:[1,0] neg_lo:[0,1] neg_hi:[0,1]
	v_pk_add_f32 v[86:87], v[86:87], v[212:213] op_sel_hi:[1,0] neg_lo:[0,1] neg_hi:[0,1]
	v_pk_add_f32 v[88:89], v[88:89], v[212:213] op_sel_hi:[1,0] neg_lo:[0,1] neg_hi:[0,1]
	v_pk_add_f32 v[90:91], v[90:91], v[212:213] op_sel_hi:[1,0] neg_lo:[0,1] neg_hi:[0,1]
	v_pk_add_f32 v[92:93], v[92:93], v[212:213] op_sel_hi:[1,0] neg_lo:[0,1] neg_hi:[0,1]
	v_pk_add_f32 v[94:95], v[94:95], v[212:213] op_sel_hi:[1,0] neg_lo:[0,1] neg_hi:[0,1]
	v_mul_f32_e32 v208, v208, v217
	v_mul_f32_e32 v209, v209, v217
	s_waitcnt lgkmcnt(0)
	ds_write_b32 v220, v217
	s_waitcnt lgkmcnt(0)
	ds_read_b128 v[116:119], v221 offset:0
	ds_read_b128 v[120:123], v221 offset:32
	ds_read_b128 v[124:127], v221 offset:64
	ds_read_b128 v[128:131], v221 offset:96
	s_waitcnt lgkmcnt(0)
	v_mul_f32_e32 v0, v0, v116
	v_mul_f32_e32 v1, v1, v117
	v_mul_f32_e32 v2, v2, v118
	v_mul_f32_e32 v3, v3, v119
	v_mul_f32_e32 v4, v4, v120
	v_mul_f32_e32 v5, v5, v121
	v_mul_f32_e32 v6, v6, v122
	v_mul_f32_e32 v7, v7, v123
	v_mul_f32_e32 v8, v8, v124
	v_mul_f32_e32 v9, v9, v125
	v_mul_f32_e32 v10, v10, v126
	v_mul_f32_e32 v11, v11, v127
	v_mul_f32_e32 v12, v12, v128
	v_mul_f32_e32 v13, v13, v129
	v_mul_f32_e32 v14, v14, v130
	v_mul_f32_e32 v15, v15, v131
	v_mul_f32_e32 v16, v16, v116
	v_mul_f32_e32 v17, v17, v117
	v_mul_f32_e32 v18, v18, v118
	v_mul_f32_e32 v19, v19, v119
	v_mul_f32_e32 v20, v20, v120
	v_mul_f32_e32 v21, v21, v121
	v_mul_f32_e32 v22, v22, v122
	v_mul_f32_e32 v23, v23, v123
	v_mul_f32_e32 v24, v24, v124
	v_mul_f32_e32 v25, v25, v125
	v_mul_f32_e32 v26, v26, v126
	v_mul_f32_e32 v27, v27, v127
	v_mul_f32_e32 v28, v28, v128
	v_mul_f32_e32 v29, v29, v129
	v_mul_f32_e32 v30, v30, v130
	v_mul_f32_e32 v31, v31, v131
	v_mul_f32_e32 v32, v32, v116
	v_mul_f32_e32 v33, v33, v117
	v_mul_f32_e32 v34, v34, v118
	v_mul_f32_e32 v35, v35, v119
	v_mul_f32_e32 v36, v36, v120
	v_mul_f32_e32 v37, v37, v121
	v_mul_f32_e32 v38, v38, v122
	v_mul_f32_e32 v39, v39, v123
	v_mul_f32_e32 v40, v40, v124
	v_mul_f32_e32 v41, v41, v125
	v_mul_f32_e32 v42, v42, v126
	v_mul_f32_e32 v43, v43, v127
	v_mul_f32_e32 v44, v44, v128
	v_mul_f32_e32 v45, v45, v129
	v_mul_f32_e32 v46, v46, v130
	v_mul_f32_e32 v47, v47, v131
	v_mul_f32_e32 v48, v48, v116
	v_mul_f32_e32 v49, v49, v117
	v_mul_f32_e32 v50, v50, v118
	v_mul_f32_e32 v51, v51, v119
	v_mul_f32_e32 v52, v52, v120
	v_mul_f32_e32 v53, v53, v121
	v_mul_f32_e32 v54, v54, v122
	v_mul_f32_e32 v55, v55, v123
	v_mul_f32_e32 v56, v56, v124
	v_mul_f32_e32 v57, v57, v125
	v_mul_f32_e32 v58, v58, v126
	v_mul_f32_e32 v59, v59, v127
	v_mul_f32_e32 v60, v60, v128
	v_mul_f32_e32 v61, v61, v129
	v_mul_f32_e32 v62, v62, v130
	v_mul_f32_e32 v63, v63, v131
	s_branch .Lat2_back_8

.Lat2_done_5:
	s_mov_b32 m0, s24
	s_waitcnt lgkmcnt(0)
	s_barrier
